# baseline (speedup 1.0000x reference)
; __device__ __forceinline__ void p0_prologue(const Params& p, LAS unsigned char* lds, int tid) {
;     ...
;     for (int it = gw; it < I_LAYER * DEPTH; it += NGW) {
;         const int l = it / I_LAYER; int r = it % I_LAYER;
;         unsigned char* wl = p.ws + (size_t)l * LAYER_BYTES;
.Lmy_w181:
	s_or_b64 exec, exec, s[4:5]
	s_waitcnt vmcnt(0) lgkmcnt(0)
	v_readlane_b32 s0, v140, 0
	v_readlane_b32 s1, v140, 1
	v_readlane_b32 s2, v140, 2
	v_readlane_b32 s3, v140, 3
	v_readlane_b32 s4, v140, 4
	v_readlane_b32 s5, v140, 5
	v_readlane_b32 s6, v140, 6
	v_readlane_b32 s7, v140, 7
	v_readlane_b32 s8, v140, 8
	v_readlane_b32 s9, v140, 9
	v_readlane_b32 s10, v140, 10
	v_readlane_b32 s11, v140, 11
	v_readlane_b32 s12, v140, 12
	v_readlane_b32 s13, v140, 13
	v_readlane_b32 s14, v140, 14
	v_readlane_b32 s15, v140, 15
	v_readlane_b32 s16, v140, 16
	v_readlane_b32 s17, v140, 17
	v_readlane_b32 s18, v140, 18
	v_readlane_b32 s19, v140, 19
	v_readlane_b32 s20, v140, 20
	v_readlane_b32 s21, v140, 21
	v_readlane_b32 s22, v140, 22
	v_readlane_b32 s23, v140, 23
	v_readlane_b32 s24, v140, 24
	v_readlane_b32 s25, v140, 25
	v_readlane_b32 s26, v140, 26
	v_readlane_b32 s27, v140, 27
	v_readlane_b32 s28, v140, 28
	v_readlane_b32 s29, v140, 29
	v_readlane_b32 s30, v140, 30
	v_readlane_b32 s31, v140, 31
	v_readlane_b32 s32, v140, 32
	v_readlane_b32 s33, v140, 33
	v_readlane_b32 s34, v140, 34
	v_readlane_b32 s35, v140, 35
	v_readlane_b32 s36, v140, 36
	v_readlane_b32 s37, v140, 37
	v_readlane_b32 s38, v140, 38
	v_readlane_b32 s39, v140, 39
	v_readlane_b32 s40, v140, 40
	v_readlane_b32 s41, v140, 41
	v_readlane_b32 s42, v140, 42
	v_readlane_b32 s43, v140, 43
	v_readlane_b32 s44, v140, 44
	v_readlane_b32 s45, v140, 45
	v_readlane_b32 s46, v140, 46
	v_readlane_b32 s47, v140, 47
	v_readlane_b32 s48, v140, 48
	v_readlane_b32 s49, v140, 49
	v_readlane_b32 s50, v140, 50
	v_readlane_b32 s51, v140, 51
	v_readlane_b32 s52, v140, 52
	v_readlane_b32 s53, v140, 53
	v_readlane_b32 s54, v140, 54
	v_readlane_b32 s55, v140, 55
	v_readlane_b32 s56, v140, 56
	v_readlane_b32 s57, v140, 57
	v_readlane_b32 s58, v140, 58
	v_readlane_b32 s59, v140, 59
	v_readlane_b32 s60, v140, 60
	v_readlane_b32 s61, v140, 61
	v_readlane_b32 s62, v140, 62
	v_readlane_b32 s63, v140, 63
	v_readlane_b32 s64, v141, 0
	v_readlane_b32 s65, v141, 1
	v_readlane_b32 s66, v141, 2
	v_readlane_b32 s67, v141, 3
	v_readlane_b32 s68, v141, 4
	v_readlane_b32 s69, v141, 5
	v_readlane_b32 s70, v141, 6
	v_readlane_b32 s71, v141, 7
	v_readlane_b32 s72, v141, 8
	v_readlane_b32 s73, v141, 9
	v_readlane_b32 s74, v141, 10
	v_readlane_b32 s75, v141, 11
	v_readlane_b32 s76, v141, 12
	v_readlane_b32 s77, v141, 13
	v_readlane_b32 s78, v141, 14
	v_readlane_b32 s79, v141, 15
	v_readlane_b32 s80, v141, 16
	v_readlane_b32 s81, v141, 17
	v_readlane_b32 s82, v141, 18
	v_readlane_b32 s83, v141, 19
	v_readlane_b32 s84, v141, 20
	v_readlane_b32 s85, v141, 21
	v_readlane_b32 s86, v141, 22
	v_readlane_b32 s87, v141, 23
	v_readlane_b32 s88, v141, 24
	v_readlane_b32 s89, v141, 25
	v_readlane_b32 s90, v141, 26
	v_readlane_b32 s91, v141, 27
	v_readlane_b32 s92, v141, 28
	v_readlane_b32 s93, v141, 29
	v_readlane_b32 s94, v141, 30
	v_readlane_b32 s95, v141, 31
	v_readlane_b32 s96, v141, 32
	v_readlane_b32 s97, v141, 33
	v_readlane_b32 s98, v141, 40
	s_nop 3
	s_cmp_eq_u32 s98, 2
	s_cbranch_scc1 .Lmy_w_skip2
	s_branch .Lmy_w_skip1

; #define LAS __attribute__((address_space(3)))
; __device__ __forceinline__ void p0_prologue(const Params& p, LAS unsigned char* lds, int tid) {
;     ...
;     LAS unsigned* scr = (LAS unsigned*)(lds + wave * 8192);
;     const int gw = blockIdx.x * 8 + wave, NGW = gridDim.x * 8;
;     ...
;     for (int it = gw; it < I_LAYER * DEPTH; it += NGW) {
;         const int l = it / I_LAYER; int r = it % I_LAYER;
;         unsigned char* wl = p.ws + (size_t)l * LAYER_BYTES;
.LBB0_427:
	v_readlane_b32 s98, v254, 36
	v_readlane_b32 s99, v253, 34
	s_cmp_gt_u32 s98, 2
	s_cbranch_scc1 .Lmy_w_skip1
	s_cmp_lt_u32 s99, 64
	s_cbranch_scc1 .Lmy_w_skip1
	v_writelane_b32 v140, s0, 0
	v_writelane_b32 v140, s1, 1
	v_writelane_b32 v140, s2, 2
	v_writelane_b32 v140, s3, 3
	v_writelane_b32 v140, s4, 4
	v_writelane_b32 v140, s5, 5
	v_writelane_b32 v140, s6, 6
	v_writelane_b32 v140, s7, 7
	v_writelane_b32 v140, s8, 8
	v_writelane_b32 v140, s9, 9
	v_writelane_b32 v140, s10, 10
	v_writelane_b32 v140, s11, 11
	v_writelane_b32 v140, s12, 12
	v_writelane_b32 v140, s13, 13
	v_writelane_b32 v140, s14, 14
	v_writelane_b32 v140, s15, 15
	v_writelane_b32 v140, s16, 16
	v_writelane_b32 v140, s17, 17
	v_writelane_b32 v140, s18, 18
	v_writelane_b32 v140, s19, 19
	v_writelane_b32 v140, s20, 20
	v_writelane_b32 v140, s21, 21
	v_writelane_b32 v140, s22, 22
	v_writelane_b32 v140, s23, 23
	v_writelane_b32 v140, s24, 24
	v_writelane_b32 v140, s25, 25
	v_writelane_b32 v140, s26, 26
	v_writelane_b32 v140, s27, 27
	v_writelane_b32 v140, s28, 28
	v_writelane_b32 v140, s29, 29
	v_writelane_b32 v140, s30, 30
	v_writelane_b32 v140, s31, 31
	v_writelane_b32 v140, s32, 32
	v_writelane_b32 v140, s33, 33
	v_writelane_b32 v140, s34, 34
	v_writelane_b32 v140, s35, 35
	v_writelane_b32 v140, s36, 36
	v_writelane_b32 v140, s37, 37
	v_writelane_b32 v140, s38, 38
	v_writelane_b32 v140, s39, 39
	v_writelane_b32 v140, s40, 40
	v_writelane_b32 v140, s41, 41
	v_writelane_b32 v140, s42, 42
	v_writelane_b32 v140, s43, 43
	v_writelane_b32 v140, s44, 44
	v_writelane_b32 v140, s45, 45
	v_writelane_b32 v140, s46, 46
	v_writelane_b32 v140, s47, 47
	v_writelane_b32 v140, s48, 48
	v_writelane_b32 v140, s49, 49
	v_writelane_b32 v140, s50, 50
	v_writelane_b32 v140, s51, 51
	v_writelane_b32 v140, s52, 52
	v_writelane_b32 v140, s53, 53
	v_writelane_b32 v140, s54, 54
	v_writelane_b32 v140, s55, 55
	v_writelane_b32 v140, s56, 56
	v_writelane_b32 v140, s57, 57
	v_writelane_b32 v140, s58, 58
	v_writelane_b32 v140, s59, 59
	v_writelane_b32 v140, s60, 60
	v_writelane_b32 v140, s61, 61
	v_writelane_b32 v140, s62, 62
	v_writelane_b32 v140, s63, 63
	v_writelane_b32 v141, s64, 0
	v_writelane_b32 v141, s65, 1
	v_writelane_b32 v141, s66, 2
	v_writelane_b32 v141, s67, 3
	v_writelane_b32 v141, s68, 4
	v_writelane_b32 v141, s69, 5
	v_writelane_b32 v141, s70, 6
	v_writelane_b32 v141, s71, 7
	v_writelane_b32 v141, s72, 8
	v_writelane_b32 v141, s73, 9
	v_writelane_b32 v141, s74, 10
	v_writelane_b32 v141, s75, 11
	v_writelane_b32 v141, s76, 12
	v_writelane_b32 v141, s77, 13
	v_writelane_b32 v141, s78, 14
	v_writelane_b32 v141, s79, 15
	v_writelane_b32 v141, s80, 16
	v_writelane_b32 v141, s81, 17
	v_writelane_b32 v141, s82, 18
	v_writelane_b32 v141, s83, 19
	v_writelane_b32 v141, s84, 20
	v_writelane_b32 v141, s85, 21
	v_writelane_b32 v141, s86, 22
	v_writelane_b32 v141, s87, 23
	v_writelane_b32 v141, s88, 24
	v_writelane_b32 v141, s89, 25
	v_writelane_b32 v141, s90, 26
	v_writelane_b32 v141, s91, 27
	v_writelane_b32 v141, s92, 28
	v_writelane_b32 v141, s93, 29
	v_writelane_b32 v141, s94, 30
	v_writelane_b32 v141, s95, 31
	v_writelane_b32 v141, s96, 32
	v_writelane_b32 v141, s97, 33
	s_mov_b32 s0, 1
	v_writelane_b32 v141, s0, 40
	s_add_i32 s98, s98, 1
	s_mul_i32 s98, s98, 0x2a00
	s_sub_i32 s1, s99, 64
	s_lshl_b32 s1, s1, 3
	s_add_i32 s0, s98, s1
	s_add_i32 s98, s98, 8192
	s_movk_i32 s10, 0x600
	v_and_b32_e32 v34, 63, v201
	v_lshrrev_b32_e32 v35, 6, v201
	v_lshlrev_b32_e32 v36, 3, v201
	v_add_u32_e32 v90, s0, v35
	s_add_i32 s99, s98, -1
	v_readlane_b32 s62, v255, 8
	v_readlane_b32 s63, v255, 9
	s_branch .Lmy_w_entry

; __device__ __forceinline__ void xcd_barrier(const XcdBarrier& b) {
;     asm volatile("s_waitcnt vmcnt(0)" ::: "memory");
;     __syncthreads();
;     if (threadIdx.x == 0) {
;         unsigned* bar = b.bar;
;         __builtin_amdgcn_s_waitcnt(0);
;         unsigned nloc = b.st[0], nx = b.st[1];
;         if (nloc == 0u) { xcd_barrier_complete(bar, b.x, nloc, nx); b.st[0] = nloc; b.st[1] = nx; }
; __device__ __forceinline__ void p0_prologue(const Params& p, LAS unsigned char* lds, int tid) {
;     ...
;     for (int it = gw; it < I_LAYER * DEPTH; it += NGW) {
;         const int l = it / I_LAYER; int r = it % I_LAYER;
;         unsigned char* wl = p.ws + (size_t)l * LAYER_BYTES;
.LBB0_971:
	s_barrier
	v_readlane_b32 s98, v254, 36
	v_readlane_b32 s99, v253, 34
	s_cmp_gt_u32 s98, 2
	s_cbranch_scc1 .Lmy_w_skip2
	v_writelane_b32 v140, s0, 0
	v_writelane_b32 v140, s1, 1
	v_writelane_b32 v140, s2, 2
	v_writelane_b32 v140, s3, 3
	v_writelane_b32 v140, s4, 4
	v_writelane_b32 v140, s5, 5
	v_writelane_b32 v140, s6, 6
	v_writelane_b32 v140, s7, 7
	v_writelane_b32 v140, s8, 8
	v_writelane_b32 v140, s9, 9
	v_writelane_b32 v140, s10, 10
	v_writelane_b32 v140, s11, 11
	v_writelane_b32 v140, s12, 12
	v_writelane_b32 v140, s13, 13
	v_writelane_b32 v140, s14, 14
	v_writelane_b32 v140, s15, 15
	v_writelane_b32 v140, s16, 16
	v_writelane_b32 v140, s17, 17
	v_writelane_b32 v140, s18, 18
	v_writelane_b32 v140, s19, 19
	v_writelane_b32 v140, s20, 20
	v_writelane_b32 v140, s21, 21
	v_writelane_b32 v140, s22, 22
	v_writelane_b32 v140, s23, 23
	v_writelane_b32 v140, s24, 24
	v_writelane_b32 v140, s25, 25
	v_writelane_b32 v140, s26, 26
	v_writelane_b32 v140, s27, 27
	v_writelane_b32 v140, s28, 28
	v_writelane_b32 v140, s29, 29
	v_writelane_b32 v140, s30, 30
	v_writelane_b32 v140, s31, 31
	v_writelane_b32 v140, s32, 32
	v_writelane_b32 v140, s33, 33
	v_writelane_b32 v140, s34, 34
	v_writelane_b32 v140, s35, 35
	v_writelane_b32 v140, s36, 36
	v_writelane_b32 v140, s37, 37
	v_writelane_b32 v140, s38, 38
	v_writelane_b32 v140, s39, 39
	v_writelane_b32 v140, s40, 40
	v_writelane_b32 v140, s41, 41
	v_writelane_b32 v140, s42, 42
	v_writelane_b32 v140, s43, 43
	v_writelane_b32 v140, s44, 44
	v_writelane_b32 v140, s45, 45
	v_writelane_b32 v140, s46, 46
	v_writelane_b32 v140, s47, 47
	v_writelane_b32 v140, s48, 48
	v_writelane_b32 v140, s49, 49
	v_writelane_b32 v140, s50, 50
	v_writelane_b32 v140, s51, 51
	v_writelane_b32 v140, s52, 52
	v_writelane_b32 v140, s53, 53
	v_writelane_b32 v140, s54, 54
	v_writelane_b32 v140, s55, 55
	v_writelane_b32 v140, s56, 56
	v_writelane_b32 v140, s57, 57
	v_writelane_b32 v140, s58, 58
	v_writelane_b32 v140, s59, 59
	v_writelane_b32 v140, s60, 60
	v_writelane_b32 v140, s61, 61
	v_writelane_b32 v140, s62, 62
	v_writelane_b32 v140, s63, 63
	v_writelane_b32 v141, s64, 0
	v_writelane_b32 v141, s65, 1
	v_writelane_b32 v141, s66, 2
	v_writelane_b32 v141, s67, 3
	v_writelane_b32 v141, s68, 4
	v_writelane_b32 v141, s69, 5
	v_writelane_b32 v141, s70, 6
	v_writelane_b32 v141, s71, 7
	v_writelane_b32 v141, s72, 8
	v_writelane_b32 v141, s73, 9
	v_writelane_b32 v141, s74, 10
	v_writelane_b32 v141, s75, 11
	v_writelane_b32 v141, s76, 12
	v_writelane_b32 v141, s77, 13
	v_writelane_b32 v141, s78, 14
	v_writelane_b32 v141, s79, 15
	v_writelane_b32 v141, s80, 16
	v_writelane_b32 v141, s81, 17
	v_writelane_b32 v141, s82, 18
	v_writelane_b32 v141, s83, 19
	v_writelane_b32 v141, s84, 20
	v_writelane_b32 v141, s85, 21
	v_writelane_b32 v141, s86, 22
	v_writelane_b32 v141, s87, 23
	v_writelane_b32 v141, s88, 24
	v_writelane_b32 v141, s89, 25
	v_writelane_b32 v141, s90, 26
	v_writelane_b32 v141, s91, 27
	v_writelane_b32 v141, s92, 28
	v_writelane_b32 v141, s93, 29
	v_writelane_b32 v141, s94, 30
	v_writelane_b32 v141, s95, 31
	v_writelane_b32 v141, s96, 32
	v_writelane_b32 v141, s97, 33
	s_mov_b32 s0, 2
	v_writelane_b32 v141, s0, 40
	s_add_i32 s98, s98, 1
	s_mul_i32 s98, s98, 0x2a00
	s_lshl_b32 s1, s99, 3
	s_add_i32 s0, s98, s1
	s_add_i32 s0, s0, 8192
	s_add_i32 s98, s98, 0x2a00
	s_movk_i32 s10, 0x400
	v_and_b32_e32 v34, 63, v201
	v_lshrrev_b32_e32 v35, 6, v201
	v_lshlrev_b32_e32 v36, 3, v201
	v_add_u32_e32 v90, s0, v35
	s_add_i32 s99, s98, -1
	v_readlane_b32 s62, v255, 8
	v_readlane_b32 s63, v255, 9
	s_branch .Lmy_w_entry
.Lmy_w_skip2:
.LBB0_972:
	s_waitcnt vmcnt(0)
	s_barrier
	s_mov_b64 s[0:1], exec
	v_readlane_b32 s2, v253, 0
	v_readlane_b32 s3, v253, 1
	s_and_b64 s[2:3], s[0:1], s[2:3]
	v_readlane_b32 s88, v254, 39
	s_mov_b64 exec, s[2:3]
	s_cbranch_execz .LBB0_1040
	v_readlane_b32 s2, v254, 34
	s_waitcnt vmcnt(0) expcnt(0) lgkmcnt(0)
	s_nop 0
	v_mov_b32_e32 v0, s2
	ds_read_b32 v2, v0
	v_readlane_b32 s2, v254, 35
	s_waitcnt lgkmcnt(0)
	v_cmp_ne_u32_e32 vcc, 0, v2
	v_mov_b32_e32 v0, s2
	ds_read_b32 v0, v0
	s_cbranch_vccnz .LBB0_988
	s_mov_b32 s24, 1
	s_branch .LBB0_976
